# F1 epilogue: twiddles from v_cos_f32/v_sin_f32 instead of 32 serialized table gathers per lane
# speedup vs baseline: 1.0209x; 1.0013x over previous
.LBB0_542:
	v_mbcnt_lo_u32_b32 v136, -1, 0
	v_mbcnt_hi_u32_b32 v136, -1, v136
	s_lshl_b32 s13, s38, 4
	v_and_b32_e32 v137, 15, v136
	v_ashrrev_i32_e32 v136, 4, v136
	s_and_b32 s13, s13, 48
	v_lshlrev_b32_e32 v140, 3, v136
	v_and_or_b32 v143, v140, 8, s13
	v_readlane_b32 s13, v253, 46
	v_readlane_b32 s15, v253, 39
	v_ashrrev_i32_e32 v136, 1, v136
	v_add_u32_e32 v147, s13, v137
	s_lshl_b32 s13, s38, 2
	s_and_b32 s13, s13, -16
	s_or_b32 s13, s13, s15
	v_mul_lo_u32 v146, v143, v147
	v_add_u32_e32 v140, s13, v136
	v_lshlrev_b32_e32 v136, 6, v137
	v_and_b32_e32 v137, 0x1ff8, v146
	v_cvt_f32_u32_e32 v137, v137
	v_mul_f32_e32 v137, 0x39000000, v137
	v_add_u32_e32 v145, v146, v147
	v_cos_f32_e32 v152, v137
	v_sin_f32_e32 v153, v137
	s_nop 0
	v_and_b32_e32 v137, 0x1fff, v145
	v_cvt_f32_u32_e32 v137, v137
	v_mul_f32_e32 v137, 0x39000000, v137
	v_add_u32_e32 v144, v145, v147
	v_cos_f32_e32 v154, v137
	v_sin_f32_e32 v155, v137
	s_nop 0
	v_and_b32_e32 v137, 0x1ffe, v144
	v_cvt_f32_u32_e32 v137, v137
	v_mul_f32_e32 v137, 0x39000000, v137
	v_add_u32_e32 v142, v144, v147
	v_cos_f32_e32 v156, v137
	v_sin_f32_e32 v157, v137
	s_nop 0
	v_and_b32_e32 v137, 0x1fff, v142
	v_cvt_f32_u32_e32 v137, v137
	v_mul_f32_e32 v137, 0x39000000, v137
	v_cos_f32_e32 v158, v137
	v_sin_f32_e32 v159, v137
	s_nop 0
	s_movk_i32 s13, 0xc0
	v_lshlrev_b32_e32 v141, 7, v147
	v_and_or_b32 v160, v136, s13, v143
	v_and_b32_e32 v136, 0xfffffe00, v141
	v_add_u32_e32 v136, v136, v140
	v_ashrrev_i32_e32 v137, 31, v136
	v_lshlrev_b32_e32 v160, 2, v160
	s_mov_b64 s[20:21], -1
	s_andn2_b64 vcc, exec, s[40:41]
	v_pk_mul_f32 v[148:149], v[120:121], v[152:153] op_sel_hi:[0,1]
	v_pk_fma_f32 v[150:151], v[124:125], v[152:153], v[148:149] op_sel:[0,1,0] op_sel_hi:[1,0,1]
	v_pk_fma_f32 v[148:149], v[124:125], v[152:153], v[148:149] op_sel:[0,1,0] op_sel_hi:[0,0,1] neg_lo:[0,0,1] neg_hi:[0,0,1]
	v_cvt_pk_bf16_f32 v148, v150, v149
	v_pk_mul_f32 v[120:121], v[120:121], v[154:155] op_sel:[1,0]
	s_nop 0
	v_pk_fma_f32 v[150:151], v[124:125], v[154:155], v[120:121] op_sel:[1,1,0] op_sel_hi:[1,0,1]
	v_pk_fma_f32 v[120:121], v[124:125], v[154:155], v[120:121] op_sel:[1,1,0] op_sel_hi:[1,0,1] neg_lo:[0,0,1] neg_hi:[0,0,1]
	s_nop 0
	v_cvt_pk_bf16_f32 v149, v150, v121
	v_pk_mul_f32 v[120:121], v[122:123], v[156:157] op_sel_hi:[0,1]
	v_pk_fma_f32 v[124:125], v[126:127], v[156:157], v[120:121] op_sel:[0,1,0] op_sel_hi:[1,0,1]
	v_pk_fma_f32 v[120:121], v[126:127], v[156:157], v[120:121] op_sel:[0,1,0] op_sel_hi:[0,0,1] neg_lo:[0,0,1] neg_hi:[0,0,1]
	v_mov_b32_e32 v122, v123
	v_mov_b32_e32 v120, v127
	v_pk_mul_f32 v[122:123], v[122:123], v[158:159] op_sel_hi:[0,1]
	v_cvt_pk_bf16_f32 v150, v124, v121
	v_pk_fma_f32 v[124:125], v[120:121], v[158:159], v[122:123] op_sel:[0,1,0] op_sel_hi:[0,0,1]
	v_pk_fma_f32 v[120:121], v[120:121], v[158:159], v[122:123] op_sel:[0,1,0] op_sel_hi:[0,0,1] neg_lo:[0,0,1] neg_hi:[0,0,1]
	v_pk_mul_f32 v[122:123], v[112:113], v[152:153] op_sel_hi:[0,1]
	v_cvt_pk_bf16_f32 v151, v124, v121
	v_pk_fma_f32 v[124:125], v[116:117], v[152:153], v[122:123] op_sel:[0,1,0] op_sel_hi:[1,0,1]
	v_pk_fma_f32 v[122:123], v[116:117], v[152:153], v[122:123] op_sel:[0,1,0] op_sel_hi:[0,0,1] neg_lo:[0,0,1] neg_hi:[0,0,1]
	v_pk_mul_f32 v[112:113], v[112:113], v[154:155] op_sel:[1,0]
	v_cvt_pk_bf16_f32 v122, v124, v123
	v_pk_fma_f32 v[124:125], v[116:117], v[154:155], v[112:113] op_sel:[1,1,0] op_sel_hi:[1,0,1]
	v_pk_fma_f32 v[112:113], v[116:117], v[154:155], v[112:113] op_sel:[1,1,0] op_sel_hi:[1,0,1] neg_lo:[0,0,1] neg_hi:[0,0,1]
	v_lshlrev_b64 v[120:121], 10, v[136:137]
	v_cvt_pk_bf16_f32 v123, v124, v113
	v_pk_mul_f32 v[112:113], v[114:115], v[156:157] op_sel_hi:[0,1]
	v_pk_fma_f32 v[116:117], v[118:119], v[156:157], v[112:113] op_sel:[0,1,0] op_sel_hi:[1,0,1]
	v_pk_fma_f32 v[112:113], v[118:119], v[156:157], v[112:113] op_sel:[0,1,0] op_sel_hi:[0,0,1] neg_lo:[0,0,1] neg_hi:[0,0,1]
	v_mov_b32_e32 v114, v115
	v_mov_b32_e32 v112, v119
	v_pk_mul_f32 v[114:115], v[114:115], v[158:159] op_sel_hi:[0,1]
	v_cvt_pk_bf16_f32 v124, v116, v113
	v_pk_fma_f32 v[116:117], v[112:113], v[158:159], v[114:115] op_sel:[0,1,0] op_sel_hi:[0,0,1]
	v_pk_fma_f32 v[112:113], v[112:113], v[158:159], v[114:115] op_sel:[0,1,0] op_sel_hi:[0,0,1] neg_lo:[0,0,1] neg_hi:[0,0,1]
	v_add_u32_e32 v112, 8, v136
	v_cvt_pk_bf16_f32 v125, v116, v113
	v_ashrrev_i32_e32 v113, 31, v112
	v_lshlrev_b64 v[112:113], 10, v[112:113]
	v_lshl_add_u64 v[112:113], s[6:7], 0, v[112:113]
	v_lshl_add_u64 v[120:121], s[6:7], 0, v[120:121]
	v_lshl_add_u64 v[112:113], v[112:113], 0, v[160:161]
	v_lshl_add_u64 v[120:121], v[120:121], 0, v[160:161]
	global_store_dwordx4 v[112:113], v[122:125], off
	global_store_dwordx4 v[120:121], v[148:151], off
	s_nop 0
	v_add_u32_e32 v125, v142, v147
	v_and_b32_e32 v114, 0x1ffc, v125
	v_add_u32_e32 v124, v125, v147
	v_cvt_f32_u32_e32 v114, v114
	v_mul_f32_e32 v114, 0x39000000, v114
	v_and_b32_e32 v116, 0x1fff, v124
	v_sin_f32_e32 v115, v114
	v_cos_f32_e32 v114, v114
	s_nop 0
	v_cvt_f32_u32_e32 v116, v116
	v_mul_f32_e32 v116, 0x39000000, v116
	v_add_u32_e32 v123, v124, v147
	v_sin_f32_e32 v117, v116
	v_cos_f32_e32 v116, v116
	s_nop 0
	v_and_b32_e32 v118, 0x1ffe, v123
	v_cvt_f32_u32_e32 v118, v118
	v_mul_f32_e32 v118, 0x39000000, v118
	v_add_u32_e32 v122, v123, v147
	v_sin_f32_e32 v119, v118
	v_cos_f32_e32 v118, v118
	s_nop 0
	v_and_b32_e32 v126, 0x1fff, v122
	v_cvt_f32_u32_e32 v126, v126
	v_mul_f32_e32 v126, 0x39000000, v126
	v_sin_f32_e32 v127, v126
	v_cos_f32_e32 v126, v126
	s_nop 0
	v_pk_mul_f32 v[136:137], v[104:105], v[114:115] op_sel_hi:[0,1]
	v_pk_fma_f32 v[148:149], v[108:109], v[114:115], v[136:137] op_sel:[0,1,0] op_sel_hi:[1,0,1]
	v_pk_fma_f32 v[136:137], v[108:109], v[114:115], v[136:137] op_sel:[0,1,0] op_sel_hi:[0,0,1] neg_lo:[0,0,1] neg_hi:[0,0,1]
	v_pk_mul_f32 v[104:105], v[104:105], v[116:117] op_sel:[1,0]
	v_cvt_pk_bf16_f32 v148, v148, v137
	v_pk_fma_f32 v[136:137], v[108:109], v[116:117], v[104:105] op_sel:[1,1,0] op_sel_hi:[1,0,1]
	v_pk_fma_f32 v[104:105], v[108:109], v[116:117], v[104:105] op_sel:[1,1,0] op_sel_hi:[1,0,1] neg_lo:[0,0,1] neg_hi:[0,0,1]
	s_nop 0
	v_cvt_pk_bf16_f32 v149, v136, v105
	v_pk_mul_f32 v[104:105], v[106:107], v[118:119] op_sel_hi:[0,1]
	v_pk_fma_f32 v[108:109], v[110:111], v[118:119], v[104:105] op_sel:[0,1,0] op_sel_hi:[1,0,1]
	v_pk_fma_f32 v[104:105], v[110:111], v[118:119], v[104:105] op_sel:[0,1,0] op_sel_hi:[0,0,1] neg_lo:[0,0,1] neg_hi:[0,0,1]
	v_mov_b32_e32 v106, v107
	v_mov_b32_e32 v104, v111
	v_pk_mul_f32 v[106:107], v[106:107], v[126:127] op_sel_hi:[0,1]
	v_cvt_pk_bf16_f32 v150, v108, v105
	v_pk_fma_f32 v[108:109], v[104:105], v[126:127], v[106:107] op_sel:[0,1,0] op_sel_hi:[0,0,1]
	v_pk_fma_f32 v[104:105], v[104:105], v[126:127], v[106:107] op_sel:[0,1,0] op_sel_hi:[0,0,1] neg_lo:[0,0,1] neg_hi:[0,0,1]
	v_cvt_pk_bf16_f32 v151, v108, v105
	v_pk_mul_f32 v[104:105], v[96:97], v[114:115] op_sel_hi:[0,1]
	v_pk_fma_f32 v[106:107], v[100:101], v[114:115], v[104:105] op_sel:[0,1,0] op_sel_hi:[1,0,1]
	v_pk_fma_f32 v[104:105], v[100:101], v[114:115], v[104:105] op_sel:[0,1,0] op_sel_hi:[0,0,1] neg_lo:[0,0,1] neg_hi:[0,0,1]
	v_pk_mul_f32 v[96:97], v[96:97], v[116:117] op_sel:[1,0]
	v_cvt_pk_bf16_f32 v104, v106, v105
	v_pk_fma_f32 v[106:107], v[100:101], v[116:117], v[96:97] op_sel:[1,1,0] op_sel_hi:[1,0,1]
	v_pk_fma_f32 v[96:97], v[100:101], v[116:117], v[96:97] op_sel:[1,1,0] op_sel_hi:[1,0,1] neg_lo:[0,0,1] neg_hi:[0,0,1]
	global_store_dwordx4 v[120:121], v[148:151], off offset:16
	v_cvt_pk_bf16_f32 v105, v106, v97
	v_pk_mul_f32 v[96:97], v[98:99], v[118:119] op_sel_hi:[0,1]
	v_pk_fma_f32 v[100:101], v[102:103], v[118:119], v[96:97] op_sel:[0,1,0] op_sel_hi:[1,0,1]
	v_pk_fma_f32 v[96:97], v[102:103], v[118:119], v[96:97] op_sel:[0,1,0] op_sel_hi:[0,0,1] neg_lo:[0,0,1] neg_hi:[0,0,1]
	v_mov_b32_e32 v98, v99
	v_mov_b32_e32 v96, v103
	v_pk_mul_f32 v[98:99], v[98:99], v[126:127] op_sel_hi:[0,1]
	v_cvt_pk_bf16_f32 v106, v100, v97
	v_pk_fma_f32 v[100:101], v[96:97], v[126:127], v[98:99] op_sel:[0,1,0] op_sel_hi:[0,0,1]
	v_pk_fma_f32 v[96:97], v[96:97], v[126:127], v[98:99] op_sel:[0,1,0] op_sel_hi:[0,0,1] neg_lo:[0,0,1] neg_hi:[0,0,1]
	v_cvt_pk_bf16_f32 v107, v100, v97
	global_store_dwordx4 v[112:113], v[104:107], off offset:16
	v_add_u32_e32 v96, 0x800, v141
	v_and_b32_e32 v96, 0xfffffe00, v96
	v_lshlrev_b32_e32 v104, 4, v143
	v_add_u32_e32 v108, v146, v104
	v_and_b32_e32 v97, 0x1ff8, v108
	v_or_b32_e32 v105, 16, v104
	v_cvt_f32_u32_e32 v97, v97
	v_mul_f32_e32 v97, 0x39000000, v97
	v_add_u32_e32 v109, v145, v105
	v_cos_f32_e32 v98, v97
	v_sin_f32_e32 v99, v97
	s_nop 0
	v_and_b32_e32 v97, 0x1fff, v109
	v_or_b32_e32 v106, 32, v104
	v_cvt_f32_u32_e32 v97, v97
	v_mul_f32_e32 v97, 0x39000000, v97
	v_add_u32_e32 v110, v144, v106
	v_cos_f32_e32 v100, v97
	v_sin_f32_e32 v101, v97
	s_nop 0
	v_and_b32_e32 v97, 0x1ffe, v110
	v_or_b32_e32 v107, 48, v104
	v_cvt_f32_u32_e32 v97, v97
	v_mul_f32_e32 v97, 0x39000000, v97
	v_add_u32_e32 v111, v142, v107
	v_cos_f32_e32 v102, v97
	v_sin_f32_e32 v103, v97
	s_nop 0
	v_and_b32_e32 v97, 0x1fff, v111
	v_cvt_f32_u32_e32 v97, v97
	v_mul_f32_e32 v97, 0x39000000, v97
	v_cos_f32_e32 v116, v97
	v_sin_f32_e32 v117, v97
	s_nop 0
	v_add_u32_e32 v96, v96, v140
	v_ashrrev_i32_e32 v97, 31, v96
	v_pk_mul_f32 v[112:113], v[88:89], v[98:99] op_sel_hi:[0,1]
	v_pk_fma_f32 v[114:115], v[92:93], v[98:99], v[112:113] op_sel:[0,1,0] op_sel_hi:[1,0,1]
	v_pk_fma_f32 v[112:113], v[92:93], v[98:99], v[112:113] op_sel:[0,1,0] op_sel_hi:[0,0,1] neg_lo:[0,0,1] neg_hi:[0,0,1]
	v_cvt_pk_bf16_f32 v112, v114, v113
	v_pk_mul_f32 v[88:89], v[88:89], v[100:101] op_sel:[1,0]
	s_nop 0
	v_pk_fma_f32 v[114:115], v[92:93], v[100:101], v[88:89] op_sel:[1,1,0] op_sel_hi:[1,0,1]
	v_pk_fma_f32 v[88:89], v[92:93], v[100:101], v[88:89] op_sel:[1,1,0] op_sel_hi:[1,0,1] neg_lo:[0,0,1] neg_hi:[0,0,1]
	s_nop 0
	v_cvt_pk_bf16_f32 v113, v114, v89
	v_pk_mul_f32 v[88:89], v[90:91], v[102:103] op_sel_hi:[0,1]
	v_pk_fma_f32 v[92:93], v[94:95], v[102:103], v[88:89] op_sel:[0,1,0] op_sel_hi:[1,0,1]
	v_pk_fma_f32 v[88:89], v[94:95], v[102:103], v[88:89] op_sel:[0,1,0] op_sel_hi:[0,0,1] neg_lo:[0,0,1] neg_hi:[0,0,1]
	v_mov_b32_e32 v90, v91
	v_mov_b32_e32 v88, v95
	v_pk_mul_f32 v[90:91], v[90:91], v[116:117] op_sel_hi:[0,1]
	v_cvt_pk_bf16_f32 v114, v92, v89
	v_pk_fma_f32 v[92:93], v[88:89], v[116:117], v[90:91] op_sel:[0,1,0] op_sel_hi:[0,0,1]
	v_pk_fma_f32 v[88:89], v[88:89], v[116:117], v[90:91] op_sel:[0,1,0] op_sel_hi:[0,0,1] neg_lo:[0,0,1] neg_hi:[0,0,1]
	v_pk_mul_f32 v[90:91], v[80:81], v[98:99] op_sel_hi:[0,1]
	v_cvt_pk_bf16_f32 v115, v92, v89
	v_pk_fma_f32 v[92:93], v[84:85], v[98:99], v[90:91] op_sel:[0,1,0] op_sel_hi:[1,0,1]
	v_pk_fma_f32 v[90:91], v[84:85], v[98:99], v[90:91] op_sel:[0,1,0] op_sel_hi:[0,0,1] neg_lo:[0,0,1] neg_hi:[0,0,1]
	v_pk_mul_f32 v[80:81], v[80:81], v[100:101] op_sel:[1,0]
	v_cvt_pk_bf16_f32 v90, v92, v91
	v_pk_fma_f32 v[92:93], v[84:85], v[100:101], v[80:81] op_sel:[1,1,0] op_sel_hi:[1,0,1]
	v_pk_fma_f32 v[80:81], v[84:85], v[100:101], v[80:81] op_sel:[1,1,0] op_sel_hi:[1,0,1] neg_lo:[0,0,1] neg_hi:[0,0,1]
	v_lshlrev_b64 v[88:89], 10, v[96:97]
	v_cvt_pk_bf16_f32 v91, v92, v81
	v_pk_mul_f32 v[80:81], v[82:83], v[102:103] op_sel_hi:[0,1]
	v_pk_fma_f32 v[84:85], v[86:87], v[102:103], v[80:81] op_sel:[0,1,0] op_sel_hi:[1,0,1]
	v_pk_fma_f32 v[80:81], v[86:87], v[102:103], v[80:81] op_sel:[0,1,0] op_sel_hi:[0,0,1] neg_lo:[0,0,1] neg_hi:[0,0,1]
	v_mov_b32_e32 v82, v83
	v_mov_b32_e32 v80, v87
	v_pk_mul_f32 v[82:83], v[82:83], v[116:117] op_sel_hi:[0,1]
	v_cvt_pk_bf16_f32 v92, v84, v81
	v_pk_fma_f32 v[84:85], v[80:81], v[116:117], v[82:83] op_sel:[0,1,0] op_sel_hi:[0,0,1]
	v_pk_fma_f32 v[80:81], v[80:81], v[116:117], v[82:83] op_sel:[0,1,0] op_sel_hi:[0,0,1] neg_lo:[0,0,1] neg_hi:[0,0,1]
	v_add_u32_e32 v80, 8, v96
	v_cvt_pk_bf16_f32 v93, v84, v81
	v_ashrrev_i32_e32 v81, 31, v80
	v_lshlrev_b64 v[80:81], 10, v[80:81]
	v_lshl_add_u64 v[80:81], s[6:7], 0, v[80:81]
	v_lshl_add_u64 v[80:81], v[80:81], 0, v[160:161]
	v_lshl_add_u64 v[88:89], s[6:7], 0, v[88:89]
	global_store_dwordx4 v[80:81], v[90:93], off
	v_lshl_add_u64 v[88:89], v[88:89], 0, v[160:161]
	global_store_dwordx4 v[88:89], v[112:115], off
	v_or_b32_e32 v90, 64, v104
	v_add_u32_e32 v94, v125, v90
	v_or_b32_e32 v91, 0x50, v104
	v_and_b32_e32 v82, 0x1ffc, v94
	v_add_u32_e32 v95, v124, v91
	v_cvt_f32_u32_e32 v82, v82
	v_mul_f32_e32 v82, 0x39000000, v82
	v_and_b32_e32 v84, 0x1fff, v95
	v_or_b32_e32 v92, 0x60, v104
	v_sin_f32_e32 v83, v82
	v_cos_f32_e32 v82, v82
	s_nop 0
	v_cvt_f32_u32_e32 v84, v84
	v_mul_f32_e32 v84, 0x39000000, v84
	v_add_u32_e32 v96, v123, v92
	v_sin_f32_e32 v85, v84
	v_cos_f32_e32 v84, v84
	s_nop 0
	v_and_b32_e32 v86, 0x1ffe, v96
	v_or_b32_e32 v93, 0x70, v104
	v_cvt_f32_u32_e32 v86, v86
	v_mul_f32_e32 v86, 0x39000000, v86
	v_add_u32_e32 v97, v122, v93
	v_sin_f32_e32 v87, v86
	v_cos_f32_e32 v86, v86
	s_nop 0
	v_and_b32_e32 v98, 0x1fff, v97
	v_cvt_f32_u32_e32 v98, v98
	v_mul_f32_e32 v98, 0x39000000, v98
	v_cos_f32_e32 v102, v98
	v_sin_f32_e32 v103, v98
	s_nop 0
	v_pk_mul_f32 v[98:99], v[72:73], v[82:83] op_sel_hi:[0,1]
	v_pk_fma_f32 v[100:101], v[76:77], v[82:83], v[98:99] op_sel:[0,1,0] op_sel_hi:[1,0,1]
	v_pk_fma_f32 v[98:99], v[76:77], v[82:83], v[98:99] op_sel:[0,1,0] op_sel_hi:[0,0,1] neg_lo:[0,0,1] neg_hi:[0,0,1]
	v_pk_mul_f32 v[72:73], v[72:73], v[84:85] op_sel:[1,0]
	v_cvt_pk_bf16_f32 v98, v100, v99
	v_pk_fma_f32 v[100:101], v[76:77], v[84:85], v[72:73] op_sel:[1,1,0] op_sel_hi:[1,0,1]
	v_pk_fma_f32 v[72:73], v[76:77], v[84:85], v[72:73] op_sel:[1,1,0] op_sel_hi:[1,0,1] neg_lo:[0,0,1] neg_hi:[0,0,1]
	s_nop 0
	v_cvt_pk_bf16_f32 v99, v100, v73
	v_pk_mul_f32 v[72:73], v[74:75], v[86:87] op_sel_hi:[0,1]
	v_pk_fma_f32 v[76:77], v[78:79], v[86:87], v[72:73] op_sel:[0,1,0] op_sel_hi:[1,0,1]
	v_pk_fma_f32 v[72:73], v[78:79], v[86:87], v[72:73] op_sel:[0,1,0] op_sel_hi:[0,0,1] neg_lo:[0,0,1] neg_hi:[0,0,1]
	v_mov_b32_e32 v74, v75
	v_mov_b32_e32 v72, v79
	v_pk_mul_f32 v[74:75], v[74:75], v[102:103] op_sel_hi:[0,1]
	v_cvt_pk_bf16_f32 v100, v76, v73
	v_pk_fma_f32 v[76:77], v[72:73], v[102:103], v[74:75] op_sel:[0,1,0] op_sel_hi:[0,0,1]
	v_pk_fma_f32 v[72:73], v[72:73], v[102:103], v[74:75] op_sel:[0,1,0] op_sel_hi:[0,0,1] neg_lo:[0,0,1] neg_hi:[0,0,1]
	v_cvt_pk_bf16_f32 v101, v76, v73
	v_pk_mul_f32 v[72:73], v[64:65], v[82:83] op_sel_hi:[0,1]
	v_pk_fma_f32 v[74:75], v[68:69], v[82:83], v[72:73] op_sel:[0,1,0] op_sel_hi:[1,0,1]
	v_pk_fma_f32 v[72:73], v[68:69], v[82:83], v[72:73] op_sel:[0,1,0] op_sel_hi:[0,0,1] neg_lo:[0,0,1] neg_hi:[0,0,1]
	v_pk_mul_f32 v[64:65], v[64:65], v[84:85] op_sel:[1,0]
	v_cvt_pk_bf16_f32 v72, v74, v73
	v_pk_fma_f32 v[74:75], v[68:69], v[84:85], v[64:65] op_sel:[1,1,0] op_sel_hi:[1,0,1]
	v_pk_fma_f32 v[64:65], v[68:69], v[84:85], v[64:65] op_sel:[1,1,0] op_sel_hi:[1,0,1] neg_lo:[0,0,1] neg_hi:[0,0,1]
	global_store_dwordx4 v[88:89], v[98:101], off offset:16
	v_cvt_pk_bf16_f32 v73, v74, v65
	v_pk_mul_f32 v[64:65], v[66:67], v[86:87] op_sel_hi:[0,1]
	v_pk_fma_f32 v[68:69], v[70:71], v[86:87], v[64:65] op_sel:[0,1,0] op_sel_hi:[1,0,1]
	v_pk_fma_f32 v[64:65], v[70:71], v[86:87], v[64:65] op_sel:[0,1,0] op_sel_hi:[0,0,1] neg_lo:[0,0,1] neg_hi:[0,0,1]
	v_mov_b32_e32 v66, v67
	v_mov_b32_e32 v64, v71
	v_pk_mul_f32 v[66:67], v[66:67], v[102:103] op_sel_hi:[0,1]
	v_cvt_pk_bf16_f32 v74, v68, v65
	v_pk_fma_f32 v[68:69], v[64:65], v[102:103], v[66:67] op_sel:[0,1,0] op_sel_hi:[0,0,1]
	v_pk_fma_f32 v[64:65], v[64:65], v[102:103], v[66:67] op_sel:[0,1,0] op_sel_hi:[0,0,1] neg_lo:[0,0,1] neg_hi:[0,0,1]
	v_cvt_pk_bf16_f32 v75, v68, v65
	global_store_dwordx4 v[80:81], v[72:75], off offset:16
	v_add_u32_e32 v64, 0x1000, v141
	v_and_b32_e32 v64, 0xfffffe00, v64
	v_add_u32_e32 v72, v108, v104
	v_and_b32_e32 v65, 0x1ff8, v72
	v_cvt_f32_u32_e32 v65, v65
	v_mul_f32_e32 v65, 0x39000000, v65
	v_add_u32_e32 v73, v109, v105
	v_cos_f32_e32 v66, v65
	v_sin_f32_e32 v67, v65
	s_nop 0
	v_and_b32_e32 v65, 0x1fff, v73
	v_cvt_f32_u32_e32 v65, v65
	v_mul_f32_e32 v65, 0x39000000, v65
	v_add_u32_e32 v74, v110, v106
	v_cos_f32_e32 v68, v65
	v_sin_f32_e32 v69, v65
	s_nop 0
	v_and_b32_e32 v65, 0x1ffe, v74
	v_cvt_f32_u32_e32 v65, v65
	v_mul_f32_e32 v65, 0x39000000, v65
	v_add_u32_e32 v75, v111, v107
	v_cos_f32_e32 v70, v65
	v_sin_f32_e32 v71, v65
	s_nop 0
	v_and_b32_e32 v65, 0x1fff, v75
	v_cvt_f32_u32_e32 v65, v65
	v_mul_f32_e32 v65, 0x39000000, v65
	v_cos_f32_e32 v80, v65
	v_sin_f32_e32 v81, v65
	s_nop 0
	v_add_u32_e32 v64, v64, v140
	v_ashrrev_i32_e32 v65, 31, v64
	v_pk_mul_f32 v[76:77], v[56:57], v[66:67] op_sel_hi:[0,1]
	v_pk_fma_f32 v[78:79], v[60:61], v[66:67], v[76:77] op_sel:[0,1,0] op_sel_hi:[1,0,1]
	v_pk_fma_f32 v[76:77], v[60:61], v[66:67], v[76:77] op_sel:[0,1,0] op_sel_hi:[0,0,1] neg_lo:[0,0,1] neg_hi:[0,0,1]
	v_cvt_pk_bf16_f32 v76, v78, v77
	v_pk_mul_f32 v[56:57], v[56:57], v[68:69] op_sel:[1,0]
	s_nop 0
	v_pk_fma_f32 v[78:79], v[60:61], v[68:69], v[56:57] op_sel:[1,1,0] op_sel_hi:[1,0,1]
	v_pk_fma_f32 v[56:57], v[60:61], v[68:69], v[56:57] op_sel:[1,1,0] op_sel_hi:[1,0,1] neg_lo:[0,0,1] neg_hi:[0,0,1]
	s_nop 0
	v_cvt_pk_bf16_f32 v77, v78, v57
	v_pk_mul_f32 v[56:57], v[58:59], v[70:71] op_sel_hi:[0,1]
	v_pk_fma_f32 v[60:61], v[62:63], v[70:71], v[56:57] op_sel:[0,1,0] op_sel_hi:[1,0,1]
	v_pk_fma_f32 v[56:57], v[62:63], v[70:71], v[56:57] op_sel:[0,1,0] op_sel_hi:[0,0,1] neg_lo:[0,0,1] neg_hi:[0,0,1]
	v_mov_b32_e32 v58, v59
	v_mov_b32_e32 v56, v63
	v_pk_mul_f32 v[58:59], v[58:59], v[80:81] op_sel_hi:[0,1]
	v_cvt_pk_bf16_f32 v78, v60, v57
	v_pk_fma_f32 v[60:61], v[56:57], v[80:81], v[58:59] op_sel:[0,1,0] op_sel_hi:[0,0,1]
	v_pk_fma_f32 v[56:57], v[56:57], v[80:81], v[58:59] op_sel:[0,1,0] op_sel_hi:[0,0,1] neg_lo:[0,0,1] neg_hi:[0,0,1]
	v_pk_mul_f32 v[58:59], v[48:49], v[66:67] op_sel_hi:[0,1]
	v_cvt_pk_bf16_f32 v79, v60, v57
	v_pk_fma_f32 v[60:61], v[52:53], v[66:67], v[58:59] op_sel:[0,1,0] op_sel_hi:[1,0,1]
	v_pk_fma_f32 v[58:59], v[52:53], v[66:67], v[58:59] op_sel:[0,1,0] op_sel_hi:[0,0,1] neg_lo:[0,0,1] neg_hi:[0,0,1]
	v_pk_mul_f32 v[48:49], v[48:49], v[68:69] op_sel:[1,0]
	v_cvt_pk_bf16_f32 v58, v60, v59
	v_pk_fma_f32 v[60:61], v[52:53], v[68:69], v[48:49] op_sel:[1,1,0] op_sel_hi:[1,0,1]
	v_pk_fma_f32 v[48:49], v[52:53], v[68:69], v[48:49] op_sel:[1,1,0] op_sel_hi:[1,0,1] neg_lo:[0,0,1] neg_hi:[0,0,1]
	v_lshlrev_b64 v[56:57], 10, v[64:65]
	v_cvt_pk_bf16_f32 v59, v60, v49
	v_pk_mul_f32 v[48:49], v[50:51], v[70:71] op_sel_hi:[0,1]
	v_pk_fma_f32 v[52:53], v[54:55], v[70:71], v[48:49] op_sel:[0,1,0] op_sel_hi:[1,0,1]
	v_pk_fma_f32 v[48:49], v[54:55], v[70:71], v[48:49] op_sel:[0,1,0] op_sel_hi:[0,0,1] neg_lo:[0,0,1] neg_hi:[0,0,1]
	v_mov_b32_e32 v50, v51
	v_mov_b32_e32 v48, v55
	v_pk_mul_f32 v[50:51], v[50:51], v[80:81] op_sel_hi:[0,1]
	v_cvt_pk_bf16_f32 v60, v52, v49
	v_pk_fma_f32 v[52:53], v[48:49], v[80:81], v[50:51] op_sel:[0,1,0] op_sel_hi:[0,0,1]
	v_pk_fma_f32 v[48:49], v[48:49], v[80:81], v[50:51] op_sel:[0,1,0] op_sel_hi:[0,0,1] neg_lo:[0,0,1] neg_hi:[0,0,1]
	v_add_u32_e32 v48, 8, v64
	v_cvt_pk_bf16_f32 v61, v52, v49
	v_ashrrev_i32_e32 v49, 31, v48
	v_lshlrev_b64 v[48:49], 10, v[48:49]
	v_lshl_add_u64 v[48:49], s[6:7], 0, v[48:49]
	v_lshl_add_u64 v[56:57], s[6:7], 0, v[56:57]
	v_lshl_add_u64 v[48:49], v[48:49], 0, v[160:161]
	v_lshl_add_u64 v[56:57], v[56:57], 0, v[160:161]
	global_store_dwordx4 v[48:49], v[58:61], off
	global_store_dwordx4 v[56:57], v[76:79], off
	s_nop 0
	v_add_u32_e32 v58, v94, v90
	v_and_b32_e32 v50, 0x1ffc, v58
	v_add_u32_e32 v59, v95, v91
	v_cvt_f32_u32_e32 v50, v50
	v_mul_f32_e32 v50, 0x39000000, v50
	v_and_b32_e32 v52, 0x1fff, v59
	v_sin_f32_e32 v51, v50
	v_cos_f32_e32 v50, v50
	s_nop 0
	v_cvt_f32_u32_e32 v52, v52
	v_mul_f32_e32 v52, 0x39000000, v52
	v_add_u32_e32 v60, v96, v92
	v_sin_f32_e32 v53, v52
	v_cos_f32_e32 v52, v52
	s_nop 0
	v_and_b32_e32 v54, 0x1ffe, v60
	v_cvt_f32_u32_e32 v54, v54
	v_mul_f32_e32 v54, 0x39000000, v54
	v_add_u32_e32 v61, v97, v93
	v_sin_f32_e32 v55, v54
	v_cos_f32_e32 v54, v54
	s_nop 0
	v_and_b32_e32 v62, 0x1fff, v61
	v_cvt_f32_u32_e32 v62, v62
	v_mul_f32_e32 v62, 0x39000000, v62
	v_cos_f32_e32 v66, v62
	v_sin_f32_e32 v67, v62
	s_nop 0
	v_pk_mul_f32 v[62:63], v[40:41], v[50:51] op_sel_hi:[0,1]
	v_pk_fma_f32 v[64:65], v[44:45], v[50:51], v[62:63] op_sel:[0,1,0] op_sel_hi:[1,0,1]
	v_pk_fma_f32 v[62:63], v[44:45], v[50:51], v[62:63] op_sel:[0,1,0] op_sel_hi:[0,0,1] neg_lo:[0,0,1] neg_hi:[0,0,1]
	v_pk_mul_f32 v[40:41], v[40:41], v[52:53] op_sel:[1,0]
	v_cvt_pk_bf16_f32 v62, v64, v63
	v_pk_fma_f32 v[64:65], v[44:45], v[52:53], v[40:41] op_sel:[1,1,0] op_sel_hi:[1,0,1]
	v_pk_fma_f32 v[40:41], v[44:45], v[52:53], v[40:41] op_sel:[1,1,0] op_sel_hi:[1,0,1] neg_lo:[0,0,1] neg_hi:[0,0,1]
	s_nop 0
	v_cvt_pk_bf16_f32 v63, v64, v41
	v_pk_mul_f32 v[40:41], v[42:43], v[54:55] op_sel_hi:[0,1]
	v_pk_fma_f32 v[44:45], v[46:47], v[54:55], v[40:41] op_sel:[0,1,0] op_sel_hi:[1,0,1]
	v_pk_fma_f32 v[40:41], v[46:47], v[54:55], v[40:41] op_sel:[0,1,0] op_sel_hi:[0,0,1] neg_lo:[0,0,1] neg_hi:[0,0,1]
	v_mov_b32_e32 v42, v43
	v_mov_b32_e32 v40, v47
	v_pk_mul_f32 v[42:43], v[42:43], v[66:67] op_sel_hi:[0,1]
	v_cvt_pk_bf16_f32 v64, v44, v41
	v_pk_fma_f32 v[44:45], v[40:41], v[66:67], v[42:43] op_sel:[0,1,0] op_sel_hi:[0,0,1]
	v_pk_fma_f32 v[40:41], v[40:41], v[66:67], v[42:43] op_sel:[0,1,0] op_sel_hi:[0,0,1] neg_lo:[0,0,1] neg_hi:[0,0,1]
	v_cvt_pk_bf16_f32 v65, v44, v41
	v_pk_mul_f32 v[40:41], v[32:33], v[50:51] op_sel_hi:[0,1]
	v_pk_fma_f32 v[42:43], v[36:37], v[50:51], v[40:41] op_sel:[0,1,0] op_sel_hi:[1,0,1]
	v_pk_fma_f32 v[40:41], v[36:37], v[50:51], v[40:41] op_sel:[0,1,0] op_sel_hi:[0,0,1] neg_lo:[0,0,1] neg_hi:[0,0,1]
	v_pk_mul_f32 v[32:33], v[32:33], v[52:53] op_sel:[1,0]
	v_cvt_pk_bf16_f32 v40, v42, v41
	v_pk_fma_f32 v[42:43], v[36:37], v[52:53], v[32:33] op_sel:[1,1,0] op_sel_hi:[1,0,1]
	v_pk_fma_f32 v[32:33], v[36:37], v[52:53], v[32:33] op_sel:[1,1,0] op_sel_hi:[1,0,1] neg_lo:[0,0,1] neg_hi:[0,0,1]
	global_store_dwordx4 v[56:57], v[62:65], off offset:16
	v_cvt_pk_bf16_f32 v41, v42, v33
	v_pk_mul_f32 v[32:33], v[34:35], v[54:55] op_sel_hi:[0,1]
	v_pk_fma_f32 v[36:37], v[38:39], v[54:55], v[32:33] op_sel:[0,1,0] op_sel_hi:[1,0,1]
	v_pk_fma_f32 v[32:33], v[38:39], v[54:55], v[32:33] op_sel:[0,1,0] op_sel_hi:[0,0,1] neg_lo:[0,0,1] neg_hi:[0,0,1]
	v_mov_b32_e32 v34, v35
	v_mov_b32_e32 v32, v39
	v_pk_mul_f32 v[34:35], v[34:35], v[66:67] op_sel_hi:[0,1]
	v_cvt_pk_bf16_f32 v42, v36, v33
	v_pk_fma_f32 v[36:37], v[32:33], v[66:67], v[34:35] op_sel:[0,1,0] op_sel_hi:[0,0,1]
	v_pk_fma_f32 v[32:33], v[32:33], v[66:67], v[34:35] op_sel:[0,1,0] op_sel_hi:[0,0,1] neg_lo:[0,0,1] neg_hi:[0,0,1]
	v_cvt_pk_bf16_f32 v43, v36, v33
	v_add_u32_e32 v33, v72, v104
	global_store_dwordx4 v[48:49], v[40:43], off offset:16
	v_and_b32_e32 v33, 0x1ff8, v33
	v_cvt_f32_u32_e32 v33, v33
	v_mul_f32_e32 v33, 0x39000000, v33
	v_cos_f32_e32 v34, v33
	v_sin_f32_e32 v35, v33
	s_nop 0
	v_add_u32_e32 v33, v73, v105
	v_and_b32_e32 v33, 0x1fff, v33
	v_cvt_f32_u32_e32 v33, v33
	v_mul_f32_e32 v33, 0x39000000, v33
	v_cos_f32_e32 v36, v33
	v_sin_f32_e32 v37, v33
	s_nop 0
	v_add_u32_e32 v33, v74, v106
	v_and_b32_e32 v33, 0x1ffe, v33
	v_cvt_f32_u32_e32 v33, v33
	v_mul_f32_e32 v33, 0x39000000, v33
	v_cos_f32_e32 v38, v33
	v_sin_f32_e32 v39, v33
	s_nop 0
	v_add_u32_e32 v33, v75, v107
	v_and_b32_e32 v33, 0x1fff, v33
	v_cvt_f32_u32_e32 v33, v33
	v_mul_f32_e32 v33, 0x39000000, v33
	v_cos_f32_e32 v44, v33
	v_sin_f32_e32 v45, v33
	s_nop 0
	v_add_u32_e32 v32, 0x1800, v141
	v_and_b32_e32 v32, 0xfffffe00, v32
	v_add_u32_e32 v32, v32, v140
	v_ashrrev_i32_e32 v33, 31, v32
	v_pk_mul_f32 v[40:41], v[24:25], v[34:35] op_sel_hi:[0,1]
	v_pk_fma_f32 v[42:43], v[28:29], v[34:35], v[40:41] op_sel:[0,1,0] op_sel_hi:[1,0,1]
	v_pk_fma_f32 v[40:41], v[28:29], v[34:35], v[40:41] op_sel:[0,1,0] op_sel_hi:[0,0,1] neg_lo:[0,0,1] neg_hi:[0,0,1]
	v_cvt_pk_bf16_f32 v40, v42, v41
	v_pk_mul_f32 v[24:25], v[24:25], v[36:37] op_sel:[1,0]
	s_nop 0
	v_pk_fma_f32 v[42:43], v[28:29], v[36:37], v[24:25] op_sel:[1,1,0] op_sel_hi:[1,0,1]
	v_pk_fma_f32 v[24:25], v[28:29], v[36:37], v[24:25] op_sel:[1,1,0] op_sel_hi:[1,0,1] neg_lo:[0,0,1] neg_hi:[0,0,1]
	s_nop 0
	v_cvt_pk_bf16_f32 v41, v42, v25
	v_pk_mul_f32 v[24:25], v[26:27], v[38:39] op_sel_hi:[0,1]
	v_pk_fma_f32 v[28:29], v[30:31], v[38:39], v[24:25] op_sel:[0,1,0] op_sel_hi:[1,0,1]
	v_pk_fma_f32 v[24:25], v[30:31], v[38:39], v[24:25] op_sel:[0,1,0] op_sel_hi:[0,0,1] neg_lo:[0,0,1] neg_hi:[0,0,1]
	v_mov_b32_e32 v26, v27
	v_mov_b32_e32 v24, v31
	v_pk_mul_f32 v[26:27], v[26:27], v[44:45] op_sel_hi:[0,1]
	v_cvt_pk_bf16_f32 v42, v28, v25
	v_pk_fma_f32 v[28:29], v[24:25], v[44:45], v[26:27] op_sel:[0,1,0] op_sel_hi:[0,0,1]
	v_pk_fma_f32 v[24:25], v[24:25], v[44:45], v[26:27] op_sel:[0,1,0] op_sel_hi:[0,0,1] neg_lo:[0,0,1] neg_hi:[0,0,1]
	v_pk_mul_f32 v[26:27], v[16:17], v[34:35] op_sel_hi:[0,1]
	v_cvt_pk_bf16_f32 v43, v28, v25
	v_pk_fma_f32 v[28:29], v[20:21], v[34:35], v[26:27] op_sel:[0,1,0] op_sel_hi:[1,0,1]
	v_pk_fma_f32 v[26:27], v[20:21], v[34:35], v[26:27] op_sel:[0,1,0] op_sel_hi:[0,0,1] neg_lo:[0,0,1] neg_hi:[0,0,1]
	v_pk_mul_f32 v[16:17], v[16:17], v[36:37] op_sel:[1,0]
	v_cvt_pk_bf16_f32 v26, v28, v27
	v_pk_fma_f32 v[28:29], v[20:21], v[36:37], v[16:17] op_sel:[1,1,0] op_sel_hi:[1,0,1]
	v_pk_fma_f32 v[16:17], v[20:21], v[36:37], v[16:17] op_sel:[1,1,0] op_sel_hi:[1,0,1] neg_lo:[0,0,1] neg_hi:[0,0,1]
	v_lshlrev_b64 v[24:25], 10, v[32:33]
	v_cvt_pk_bf16_f32 v27, v28, v17
	v_pk_mul_f32 v[16:17], v[18:19], v[38:39] op_sel_hi:[0,1]
	v_pk_fma_f32 v[20:21], v[22:23], v[38:39], v[16:17] op_sel:[0,1,0] op_sel_hi:[1,0,1]
	v_pk_fma_f32 v[16:17], v[22:23], v[38:39], v[16:17] op_sel:[0,1,0] op_sel_hi:[0,0,1] neg_lo:[0,0,1] neg_hi:[0,0,1]
	v_mov_b32_e32 v18, v19
	v_mov_b32_e32 v16, v23
	v_pk_mul_f32 v[18:19], v[18:19], v[44:45] op_sel_hi:[0,1]
	v_cvt_pk_bf16_f32 v28, v20, v17
	v_pk_fma_f32 v[20:21], v[16:17], v[44:45], v[18:19] op_sel:[0,1,0] op_sel_hi:[0,0,1]
	v_pk_fma_f32 v[16:17], v[16:17], v[44:45], v[18:19] op_sel:[0,1,0] op_sel_hi:[0,0,1] neg_lo:[0,0,1] neg_hi:[0,0,1]
	v_add_u32_e32 v16, 8, v32
	v_cvt_pk_bf16_f32 v29, v20, v17
	v_ashrrev_i32_e32 v17, 31, v16
	v_lshlrev_b64 v[16:17], 10, v[16:17]
	v_lshl_add_u64 v[24:25], s[6:7], 0, v[24:25]
	v_lshl_add_u64 v[16:17], s[6:7], 0, v[16:17]
	v_lshl_add_u64 v[24:25], v[24:25], 0, v[160:161]
	v_lshl_add_u64 v[16:17], v[16:17], 0, v[160:161]
	v_add_u32_e32 v18, v58, v90
	global_store_dwordx4 v[24:25], v[40:43], off
	global_store_dwordx4 v[16:17], v[26:29], off
	v_and_b32_e32 v18, 0x1ffc, v18
	v_add_u32_e32 v20, v59, v91
	v_cvt_f32_u32_e32 v18, v18
	v_mul_f32_e32 v18, 0x39000000, v18
	v_and_b32_e32 v20, 0x1fff, v20
	v_sin_f32_e32 v19, v18
	v_cos_f32_e32 v18, v18
	s_nop 0
	v_cvt_f32_u32_e32 v20, v20
	v_mul_f32_e32 v20, 0x39000000, v20
	v_add_u32_e32 v22, v60, v92
	v_sin_f32_e32 v21, v20
	v_cos_f32_e32 v20, v20
	s_nop 0
	v_and_b32_e32 v22, 0x1ffe, v22
	v_cvt_f32_u32_e32 v22, v22
	v_mul_f32_e32 v22, 0x39000000, v22
	v_add_u32_e32 v26, v61, v93
	v_sin_f32_e32 v23, v22
	v_cos_f32_e32 v22, v22
	s_nop 0
	v_and_b32_e32 v26, 0x1fff, v26
	v_cvt_f32_u32_e32 v26, v26
	v_mul_f32_e32 v26, 0x39000000, v26
	v_sin_f32_e32 v27, v26
	v_cos_f32_e32 v26, v26
	s_nop 0
	v_pk_mul_f32 v[28:29], v[8:9], v[18:19] op_sel_hi:[0,1]
	v_pk_fma_f32 v[30:31], v[12:13], v[18:19], v[28:29] op_sel:[0,1,0] op_sel_hi:[1,0,1]
	v_pk_fma_f32 v[28:29], v[12:13], v[18:19], v[28:29] op_sel:[0,1,0] op_sel_hi:[0,0,1] neg_lo:[0,0,1] neg_hi:[0,0,1]
	v_pk_mul_f32 v[8:9], v[8:9], v[20:21] op_sel:[1,0]
	v_cvt_pk_bf16_f32 v28, v30, v29
	v_pk_fma_f32 v[30:31], v[12:13], v[20:21], v[8:9] op_sel:[1,1,0] op_sel_hi:[1,0,1]
	v_pk_fma_f32 v[8:9], v[12:13], v[20:21], v[8:9] op_sel:[1,1,0] op_sel_hi:[1,0,1] neg_lo:[0,0,1] neg_hi:[0,0,1]
	s_nop 0
	v_cvt_pk_bf16_f32 v29, v30, v9
	v_pk_mul_f32 v[8:9], v[10:11], v[22:23] op_sel_hi:[0,1]
	v_pk_fma_f32 v[12:13], v[14:15], v[22:23], v[8:9] op_sel:[0,1,0] op_sel_hi:[1,0,1]
	v_pk_fma_f32 v[8:9], v[14:15], v[22:23], v[8:9] op_sel:[0,1,0] op_sel_hi:[0,0,1] neg_lo:[0,0,1] neg_hi:[0,0,1]
	v_mov_b32_e32 v10, v11
	v_mov_b32_e32 v8, v15
	v_pk_mul_f32 v[10:11], v[10:11], v[26:27] op_sel_hi:[0,1]
	v_cvt_pk_bf16_f32 v30, v12, v9
	v_pk_fma_f32 v[12:13], v[8:9], v[26:27], v[10:11] op_sel:[0,1,0] op_sel_hi:[0,0,1]
	v_pk_fma_f32 v[8:9], v[8:9], v[26:27], v[10:11] op_sel:[0,1,0] op_sel_hi:[0,0,1] neg_lo:[0,0,1] neg_hi:[0,0,1]
	v_cvt_pk_bf16_f32 v31, v12, v9
	v_pk_mul_f32 v[8:9], v[0:1], v[18:19] op_sel_hi:[0,1]
	v_pk_fma_f32 v[10:11], v[4:5], v[18:19], v[8:9] op_sel:[0,1,0] op_sel_hi:[1,0,1]
	v_pk_fma_f32 v[8:9], v[4:5], v[18:19], v[8:9] op_sel:[0,1,0] op_sel_hi:[0,0,1] neg_lo:[0,0,1] neg_hi:[0,0,1]
	v_pk_mul_f32 v[0:1], v[0:1], v[20:21] op_sel:[1,0]
	v_cvt_pk_bf16_f32 v8, v10, v9
	v_pk_fma_f32 v[10:11], v[4:5], v[20:21], v[0:1] op_sel:[1,1,0] op_sel_hi:[1,0,1]
	v_pk_fma_f32 v[0:1], v[4:5], v[20:21], v[0:1] op_sel:[1,1,0] op_sel_hi:[1,0,1] neg_lo:[0,0,1] neg_hi:[0,0,1]
	global_store_dwordx4 v[24:25], v[28:31], off offset:16
	v_cvt_pk_bf16_f32 v9, v10, v1
	v_pk_mul_f32 v[0:1], v[2:3], v[22:23] op_sel_hi:[0,1]
	v_pk_fma_f32 v[4:5], v[6:7], v[22:23], v[0:1] op_sel:[0,1,0] op_sel_hi:[1,0,1]
	v_pk_fma_f32 v[0:1], v[6:7], v[22:23], v[0:1] op_sel:[0,1,0] op_sel_hi:[0,0,1] neg_lo:[0,0,1] neg_hi:[0,0,1]
	v_mov_b32_e32 v2, v3
	v_mov_b32_e32 v0, v7
	v_pk_mul_f32 v[2:3], v[2:3], v[26:27] op_sel_hi:[0,1]
	v_cvt_pk_bf16_f32 v10, v4, v1
	v_pk_fma_f32 v[4:5], v[0:1], v[26:27], v[2:3] op_sel:[0,1,0] op_sel_hi:[0,0,1]
	v_pk_fma_f32 v[0:1], v[0:1], v[26:27], v[2:3] op_sel:[0,1,0] op_sel_hi:[0,0,1] neg_lo:[0,0,1] neg_hi:[0,0,1]
	v_cvt_pk_bf16_f32 v11, v4, v1
	global_store_dwordx4 v[16:17], v[8:11], off offset:16
	s_cbranch_vccnz .LBB0_533
	s_and_b64 vcc, exec, s[76:77]
	s_cbranch_vccnz .LBB0_532
	s_barrier
	s_branch .LBB0_532
